# v11: v7 + gla_prep software prefetch: next item's 6 tile loads issued at loop tail (rotation)
# speedup vs baseline: 1.0015x; 1.0002x over previous
.LBB0_327:
	s_and_b64 vcc, exec, s[0:1]
	s_cbranch_vccz .LBB0_337
	v_mov_b32_e32 v0, v97
	v_readlane_b32 s0, v253, 35
	v_mbcnt_lo_u32_b32 v0, -1, v0
	v_mbcnt_hi_u32_b32 v0, -1, v0
	v_readlane_b32 s1, v253, 36
	v_add_u32_e32 v0, s65, v0
	s_andn2_b64 vcc, exec, s[0:1]
	s_cbranch_vccnz .LBB0_337
	s_ashr_i32 s67, s66, 31
	s_lshl_b64 s[0:1], s[66:67], 16
	s_add_u32 s0, s4, s0
	s_addc_u32 s1, s5, s1
	s_add_u32 s28, s0, 0xe600000
	s_mov_b32 s42, s29
	s_addc_u32 s29, s1, 0
	s_lshl_b32 s0, s30, 9
	s_ashr_i32 s1, s0, 31
	s_lshl_b64 s[0:1], s[0:1], 2
	s_add_u32 s0, s4, s0
	s_addc_u32 s1, s5, s1
	s_waitcnt lgkmcnt(0)
	v_and_b32_e32 v1, 15, v0
	s_mov_b32 s43, s30
	s_add_u32 s30, s0, 0xe620000
	v_and_b32_e32 v42, 0x7f, v0
	v_lshlrev_b32_e32 v96, 2, v1
	s_mov_b32 s44, s31
	s_addc_u32 s31, s1, 0
	v_ashrrev_i32_e32 v11, 7, v0
	v_lshl_add_u64 v[2:3], s[4:5], 0, v[96:97]
	s_mov_b64 s[0:1], 0x26800000
	v_lshlrev_b32_e32 v96, 4, v1
	v_lshl_add_u32 v45, v42, 2, 0
	v_lshlrev_b32_e32 v1, 1, v42
	v_lshlrev_b32_e32 v16, 7, v42
	v_mov_b32_e32 v17, v97
	v_add_u32_e32 v12, 0x200, v0
	v_lshl_add_u64 v[4:5], v[2:3], 0, s[0:1]
	v_lshlrev_b32_e32 v2, 4, v11
	v_sub_u32_e32 v10, v45, v1
	v_lshl_add_u64 v[8:9], s[4:5], 0, v[16:17]
	v_ashrrev_i32_e32 v46, 4, v0
	s_movk_i32 s4, 0x110
	v_ashrrev_i32_e32 v47, 4, v12
	s_movk_i32 s12, 0x1100
	v_lshl_add_u64 v[6:7], s[6:7], 0, v[96:97]
	v_lshl_add_u32 v43, v11, 10, 0
	v_ashrrev_i32_e32 v3, 31, v2
	v_mul_lo_u32 v23, v46, s4
	v_mul_lo_u32 v24, v47, s4
	v_cmp_lt_i32_e64 s[4:5], 0, v11
	v_cmp_lt_i32_e64 s[6:7], 1, v11
	v_cmp_lt_i32_e64 s[18:19], 2, v11
	v_cmp_lt_i32_e64 s[20:21], 3, v11
	v_mad_u64_u32 v[10:11], s[12:13], v11, s12, v[10:11]
	v_sub_u32_e32 v14, 0, v2
	v_lshlrev_b64 v[2:3], 1, v[2:3]
	v_readlane_b32 s12, v254, 19
	v_lshl_add_u64 v[8:9], v[8:9], 0, v[2:3]
	s_mov_b64 s[0:1], 0x22800000
	v_mov_b32_e32 v1, v97
	v_readlane_b32 s13, v254, 20
	v_ashrrev_i32_e32 v15, 31, v14
	v_lshl_add_u64 v[8:9], v[8:9], 0, s[0:1]
	s_movk_i32 s0, 0x80
	v_lshl_add_u64 v[12:13], v[0:1], 2, s[12:13]
	v_readlane_b32 s12, v254, 23
	v_lshl_add_u32 v44, v0, 2, 0
	v_cmp_gt_u32_e64 s[0:1], s0, v0
	v_lshl_add_u64 v[0:1], v[14:15], 1, v[16:17]
	v_readlane_b32 s13, v254, 24
	v_lshlrev_b32_e32 v18, 7, v46
	v_ashrrev_i32_e32 v19, 31, v18
	v_lshl_add_u64 v[14:15], s[12:13], 0, v[0:1]
	v_readlane_b32 s12, v254, 29
	v_lshl_add_u64 v[0:1], v[16:17], 0, v[2:3]
	v_readlane_b32 s13, v254, 30
	v_lshlrev_b32_e32 v20, 7, v47
	v_ashrrev_i32_e32 v21, 31, v20
	v_lshl_add_u64 v[16:17], s[12:13], 0, v[0:1]
	v_lshlrev_b64 v[0:1], 1, v[18:19]
	v_readlane_b32 s12, v254, 27
	v_or_b32_e32 v0, v0, v96
	v_readlane_b32 s13, v254, 28
	v_add_u32_e32 v22, 0, v96
	s_mov_b64 s[52:53], s[70:71]
	v_lshl_add_u64 v[18:19], s[12:13], 0, v[0:1]
	v_lshlrev_b64 v[0:1], 1, v[20:21]
	v_or_b32_e32 v0, v0, v96
	s_mov_b64 s[50:51], s[72:73]
	v_lshl_add_u64 v[20:21], s[12:13], 0, v[0:1]
	v_add_u32_e32 v11, v22, v23
	s_waitcnt vmcnt(0)
	v_add_u32_e32 v48, v22, v24
	v_readlane_b32 s14, v254, 34
	v_readlane_b32 s15, v253, 33
	v_readlane_b32 s34, v254, 32
	v_readlane_b32 s35, v254, 33
	s_nop 3
	s_ashr_i32 s35, s34, 11
	s_cmpk_lt_u32 s34, 0x800
	s_cselect_b64 vcc, -1, 0
	s_and_b32 s38, s14, 0x7c0
	s_xor_b32 s39, s38, 0x7ff
	v_sub_u32_e32 v0, s39, v46
	v_add_u32_e32 v1, s38, v46
	s_and_b32 s36, s14, 0x7800
	v_cndmask_b32_e32 v0, v0, v1, vcc
	s_lshl_b32 s12, s35, 4
	v_add_u32_e32 v0, s36, v0
	s_ashr_i32 s13, s12, 31
	v_ashrrev_i32_e32 v1, 31, v0
	v_lshl_add_u64 v[22:23], s[12:13], 2, v[4:5]
	v_lshlrev_b64 v[2:3], 7, v[0:1]
	v_lshl_add_u64 v[2:3], v[22:23], 0, v[2:3]
	global_load_dword v80, v[2:3], off
	s_and_b32 s37, s15, 0x180
	s_lshl_b32 s46, s37, 1
	v_lshl_add_u64 v[24:25], v[6:7], 0, s[46:47]
	v_lshlrev_b64 v[0:1], 11, v[0:1]
	v_lshl_add_u64 v[26:27], v[24:25], 0, v[0:1]
	s_lshl_b32 s40, s35, 13
	s_or_b32 s40, s40, s37
	s_movk_i32 s12, 0x1000
	s_lshl_b32 s35, s35, 9
	s_or_b32 s35, s35, s37
	s_mov_b32 s37, 0x7f800000
	s_cmpk_gt_u32 s34, 0x7ff
	global_load_dwordx4 v[64:67], v[26:27], off
	global_load_dwordx4 v[68:71], v[26:27], off offset:1024
	v_sub_u32_e32 v0, s39, v47
	v_add_u32_e32 v1, s38, v47
	v_cndmask_b32_e32 v0, v0, v1, vcc
	v_add_u32_e32 v0, s36, v0
	v_ashrrev_i32_e32 v1, 31, v0
	v_lshlrev_b64 v[2:3], 7, v[0:1]
	v_lshl_add_u64 v[2:3], v[22:23], 0, v[2:3]
	global_load_dword v81, v[2:3], off
	v_lshlrev_b64 v[0:1], 11, v[0:1]
	v_lshl_add_u64 v[22:23], v[24:25], 0, v[0:1]
	s_mov_b32 s36, 0x3f317217
	global_load_dwordx4 v[72:75], v[22:23], off
	global_load_dwordx4 v[76:79], v[22:23], off offset:1024
	s_branch .LBB0_331
.LBB0_330:
	s_or_b64 exec, exec, s[12:13]
	s_waitcnt lgkmcnt(0)
	s_barrier
	ds_read_b128 v[0:3], v11 offset:43008
	v_lshl_add_u64 v[22:23], v[18:19], 0, s[26:27]
	v_add_co_u32_e32 v24, vcc, 0x1a800000, v22
	v_readlane_b32 s12, v254, 21
	s_nop 0
	v_addc_co_u32_e32 v25, vcc, 0, v23, vcc
	s_waitcnt lgkmcnt(0)
	global_store_dwordx4 v[24:25], v[0:3], off
	ds_read_b128 v[0:3], v11 offset:60416
	v_add_co_u32_e32 v22, vcc, 0x1e800000, v22
	v_readlane_b32 s13, v254, 22
	s_nop 0
	v_addc_co_u32_e32 v23, vcc, 0, v23, vcc
	s_waitcnt lgkmcnt(0)
	global_store_dwordx4 v[22:23], v[0:3], off
	ds_read_b128 v[0:3], v48 offset:43008
	v_lshl_add_u64 v[22:23], v[20:21], 0, s[26:27]
	v_add_co_u32_e32 v24, vcc, 0x1a800000, v22
	v_lshl_add_u64 v[12:13], v[12:13], 0, s[12:13]
	s_nop 0
	v_addc_co_u32_e32 v25, vcc, 0, v23, vcc
	v_readlane_b32 s12, v254, 25
	s_waitcnt lgkmcnt(0)
	global_store_dwordx4 v[24:25], v[0:3], off
	ds_read_b128 v[0:3], v48 offset:60416
	v_readlane_b32 s13, v254, 26
	v_add_co_u32_e32 v22, vcc, 0x1e800000, v22
	s_nop 0
	v_lshl_add_u64 v[14:15], v[14:15], 0, s[12:13]
	v_lshl_add_u64 v[16:17], v[16:17], 0, s[12:13]
	v_lshl_add_u64 v[18:19], v[18:19], 0, s[12:13]
	v_lshl_add_u64 v[20:21], v[20:21], 0, s[12:13]
	v_readlane_b32 s12, v254, 18
	s_add_i32 s15, s15, s12
	v_readlane_b32 s12, v254, 35
	s_add_i32 s34, s34, s10
	s_add_i32 s14, s14, s12
	v_addc_co_u32_e32 v23, vcc, 0, v23, vcc
	s_waitcnt lgkmcnt(0)
	global_store_dwordx4 v[22:23], v[0:3], off
	s_ashr_i32 s35, s34, 11
	s_cmpk_lt_u32 s34, 0x800
	s_cselect_b64 vcc, -1, 0
	s_and_b32 s38, s14, 0x7c0
	s_xor_b32 s39, s38, 0x7ff
	v_sub_u32_e32 v0, s39, v46
	v_add_u32_e32 v1, s38, v46
	s_and_b32 s36, s14, 0x7800
	v_cndmask_b32_e32 v0, v0, v1, vcc
	s_lshl_b32 s12, s35, 4
	v_add_u32_e32 v0, s36, v0
	s_ashr_i32 s13, s12, 31
	v_ashrrev_i32_e32 v1, 31, v0
	v_lshl_add_u64 v[22:23], s[12:13], 2, v[4:5]
	v_lshlrev_b64 v[2:3], 7, v[0:1]
	v_lshl_add_u64 v[2:3], v[22:23], 0, v[2:3]
	global_load_dword v80, v[2:3], off
	s_and_b32 s37, s15, 0x180
	s_lshl_b32 s46, s37, 1
	v_lshl_add_u64 v[24:25], v[6:7], 0, s[46:47]
	v_lshlrev_b64 v[0:1], 11, v[0:1]
	v_lshl_add_u64 v[26:27], v[24:25], 0, v[0:1]
	s_lshl_b32 s40, s35, 13
	s_or_b32 s40, s40, s37
	s_movk_i32 s12, 0x1000
	s_lshl_b32 s35, s35, 9
	s_or_b32 s35, s35, s37
	s_mov_b32 s37, 0x7f800000
	s_cmpk_gt_u32 s34, 0x7ff
	global_load_dwordx4 v[64:67], v[26:27], off
	global_load_dwordx4 v[68:71], v[26:27], off offset:1024
	v_sub_u32_e32 v0, s39, v47
	v_add_u32_e32 v1, s38, v47
	v_cndmask_b32_e32 v0, v0, v1, vcc
	v_add_u32_e32 v0, s36, v0
	v_ashrrev_i32_e32 v1, 31, v0
	v_lshlrev_b64 v[2:3], 7, v[0:1]
	v_lshl_add_u64 v[2:3], v[22:23], 0, v[2:3]
	global_load_dword v81, v[2:3], off
	v_lshlrev_b64 v[0:1], 11, v[0:1]
	v_lshl_add_u64 v[22:23], v[24:25], 0, v[0:1]
	s_mov_b32 s36, 0x3f317217
	global_load_dwordx4 v[72:75], v[22:23], off
	global_load_dwordx4 v[76:79], v[22:23], off offset:1024
	s_cmpk_gt_i32 s34, 0xfff
	s_cbranch_scc1 .LBB0_367
.LBB0_331:
	s_ashr_i32 s35, s34, 11
	s_cmpk_lt_u32 s34, 0x800
	s_cselect_b64 vcc, -1, 0
	s_and_b32 s38, s14, 0x7c0
	s_xor_b32 s39, s38, 0x7ff
	v_sub_u32_e32 v0, s39, v46
	v_add_u32_e32 v1, s38, v46
	s_and_b32 s36, s14, 0x7800
	v_cndmask_b32_e32 v0, v0, v1, vcc
	s_lshl_b32 s12, s35, 4
	v_add_u32_e32 v0, s36, v0
	s_ashr_i32 s13, s12, 31
	v_ashrrev_i32_e32 v1, 31, v0
	v_lshl_add_u64 v[22:23], s[12:13], 2, v[4:5]
	v_lshlrev_b64 v[2:3], 7, v[0:1]
	s_waitcnt lgkmcnt(0)
	s_barrier
	v_lshl_add_u64 v[2:3], v[22:23], 0, v[2:3]
	s_and_b32 s37, s15, 0x180
	s_lshl_b32 s46, s37, 1
	v_lshl_add_u64 v[24:25], v[6:7], 0, s[46:47]
	v_lshlrev_b64 v[0:1], 11, v[0:1]
	v_lshl_add_u64 v[26:27], v[24:25], 0, v[0:1]
	s_lshl_b32 s40, s35, 13
	s_or_b32 s40, s40, s37
	s_movk_i32 s12, 0x1000
	s_lshl_b32 s35, s35, 9
	s_or_b32 s35, s35, s37
	s_mov_b32 s37, 0x7f800000
	s_cmpk_gt_u32 s34, 0x7ff
	v_sub_u32_e32 v0, s39, v47
	v_add_u32_e32 v1, s38, v47
	v_cndmask_b32_e32 v0, v0, v1, vcc
	v_add_u32_e32 v0, s36, v0
	v_ashrrev_i32_e32 v1, 31, v0
	v_lshlrev_b64 v[2:3], 7, v[0:1]
	v_lshl_add_u64 v[2:3], v[22:23], 0, v[2:3]
	v_lshlrev_b64 v[0:1], 11, v[0:1]
	v_lshl_add_u64 v[22:23], v[24:25], 0, v[0:1]
	s_mov_b32 s36, 0x3f317217
	v_or_b32_e32 v0, s40, v42
	v_ashrrev_i32_e32 v1, 31, v0
	v_lshl_add_u64 v[2:3], v[0:1], 2, s[28:29]
	v_add_co_u32_e32 v0, vcc, s12, v2
	s_movk_i32 s12, 0x2000
	s_nop 0
	v_addc_co_u32_e32 v1, vcc, 0, v3, vcc
	v_add_co_u32_e32 v22, vcc, s12, v2
	s_movk_i32 s12, 0x3000
	s_nop 0
	v_addc_co_u32_e32 v23, vcc, 0, v3, vcc
	global_load_dword v30, v[2:3], off
	global_load_dword v31, v[2:3], off offset:2048
	global_load_dword v32, v[22:23], off offset:-4096
	global_load_dword v33, v[0:1], off offset:2048
	global_load_dword v26, v[22:23], off
	global_load_dword v27, v[22:23], off offset:2048
	v_add_co_u32_e32 v0, vcc, s12, v2
	s_movk_i32 s12, 0x4000
	s_nop 0
	v_addc_co_u32_e32 v1, vcc, 0, v3, vcc
	v_add_co_u32_e32 v24, vcc, s12, v2
	s_movk_i32 s12, 0x5000
	s_nop 0
	v_addc_co_u32_e32 v25, vcc, 0, v3, vcc
	global_load_dword v28, v[24:25], off offset:-4096
	global_load_dword v29, v[0:1], off offset:2048
	global_load_dword v22, v[24:25], off
	global_load_dword v23, v[24:25], off offset:2048
	v_add_co_u32_e32 v0, vcc, s12, v2
	s_movk_i32 s12, 0x6000
	s_nop 0
	v_addc_co_u32_e32 v1, vcc, 0, v3, vcc
	v_add_co_u32_e32 v34, vcc, s12, v2
	s_movk_i32 s12, 0x7000
	s_nop 0
	v_addc_co_u32_e32 v35, vcc, 0, v3, vcc
	global_load_dword v24, v[34:35], off offset:-4096
	global_load_dword v25, v[0:1], off offset:2048
	s_nop 0
	global_load_dword v0, v[34:35], off
	global_load_dword v1, v[34:35], off offset:2048
	v_add_co_u32_e32 v34, vcc, s12, v2
	s_nop 1
	v_addc_co_u32_e32 v35, vcc, 0, v3, vcc
	global_load_dword v2, v[34:35], off
	global_load_dword v3, v[34:35], off offset:2048
	v_or_b32_e32 v34, s35, v42
	v_ashrrev_i32_e32 v35, 31, v34
	v_lshl_add_u64 v[34:35], v[34:35], 2, s[30:31]
	global_load_dword v35, v[34:35], off
	s_waitcnt vmcnt(22)
	ds_write_b32 v44, v80
	s_waitcnt vmcnt(21)
	ds_write_b128 v11, v[64:67] offset:8192
	s_waitcnt vmcnt(20)
	ds_write_b128 v11, v[68:71] offset:25600
	s_waitcnt vmcnt(19)
	ds_write_b32 v44, v81 offset:2048
	s_waitcnt vmcnt(18)
	ds_write_b128 v48, v[72:75] offset:8192
	s_waitcnt vmcnt(17)
	ds_write_b128 v48, v[76:79] offset:25600
	s_waitcnt lgkmcnt(0)
	s_barrier
	ds_read_b128 v[36:39], v43
	ds_read_b128 v[50:53], v43 offset:16
	ds_read_b128 v[54:57], v43 offset:32
	ds_read_b128 v[58:61], v43 offset:48
	s_mov_b32 s35, 0xbfb8aa3b
	s_waitcnt vmcnt(0) lgkmcnt(3)
	v_fma_f32 v34, v30, v36, v35
	v_fmac_f32_e32 v34, v31, v37
	v_fmac_f32_e32 v34, v32, v38
	v_fmac_f32_e32 v34, v33, v39
	s_waitcnt lgkmcnt(2)
	v_fmac_f32_e32 v34, v26, v50
	v_fmac_f32_e32 v34, v27, v51
	v_fmac_f32_e32 v34, v28, v52
	v_fmac_f32_e32 v34, v29, v53
	s_waitcnt lgkmcnt(1)
	v_fmac_f32_e32 v34, v22, v54
	v_fmac_f32_e32 v34, v23, v55
	v_fmac_f32_e32 v34, v24, v56
	v_fmac_f32_e32 v34, v25, v57
	s_waitcnt lgkmcnt(0)
	v_pk_mul_f32 v[36:37], v[0:1], v[58:59]
	ds_read_b128 v[50:53], v43 offset:256
	v_add_f32_e32 v34, v34, v36
	v_add_f32_e32 v34, v34, v37
	v_pk_mul_f32 v[36:37], v[2:3], v[60:61]
	s_nop 0
	v_add_f32_e32 v34, v34, v36
	v_add_f32_e32 v34, v34, v37
	v_min_f32_e32 v36, 0, v34
	v_mul_f32_e64 v34, |v34|, s35
	v_exp_f32_e32 v34, v34
	s_nop 0
	v_add_f32_e32 v34, 1.0, v34
	v_cmp_gt_f32_e32 vcc, s33, v34
	s_nop 1
	v_cndmask_b32_e64 v37, 0, 32, vcc
	v_ldexp_f32 v34, v34, v37
	v_log_f32_e32 v34, v34
	s_nop 0
	v_mul_f32_e32 v37, 0x3f317217, v34
	v_fma_f32 v37, v34, s36, -v37
	v_fmac_f32_e32 v37, 0x3377d1cf, v34
	v_fmac_f32_e32 v37, 0x3f317217, v34
	v_cmp_lt_f32_e64 s[12:13], |v34|, s37
	s_nop 1
	v_cndmask_b32_e64 v34, v34, v37, s[12:13]
	v_cndmask_b32_e32 v37, 0, v179, vcc
	v_sub_f32_e32 v34, v34, v37
	v_sub_f32_e32 v34, v36, v34
	ds_read_b128 v[36:39], v43 offset:64
	s_mov_b32 s12, 0x3d800000
	v_fma_f32 v34, v34, s12, 0
	s_waitcnt lgkmcnt(0)
	v_fma_f32 v40, v30, v36, v35
	v_fmac_f32_e32 v40, v31, v37
	v_fmac_f32_e32 v40, v32, v38
	v_fmac_f32_e32 v40, v33, v39
	ds_read_b128 v[36:39], v43 offset:80
	s_waitcnt lgkmcnt(0)
	v_fmac_f32_e32 v40, v26, v36
	v_fmac_f32_e32 v40, v27, v37
	v_fmac_f32_e32 v40, v28, v38
	v_fmac_f32_e32 v40, v29, v39
	ds_read_b128 v[36:39], v43 offset:96
	s_waitcnt lgkmcnt(0)
	v_fmac_f32_e32 v40, v22, v36
	v_fmac_f32_e32 v40, v23, v37
	v_fmac_f32_e32 v40, v24, v38
	v_fmac_f32_e32 v40, v25, v39
	ds_read_b128 v[36:39], v43 offset:112
	s_waitcnt lgkmcnt(0)
	v_pk_mul_f32 v[36:37], v[0:1], v[36:37]
	s_nop 0
	v_add_f32_e32 v36, v40, v36
	v_add_f32_e32 v40, v36, v37
	v_pk_mul_f32 v[36:37], v[2:3], v[38:39]
	s_nop 0
	v_add_f32_e32 v36, v40, v36
	v_add_f32_e32 v36, v36, v37
	v_min_f32_e32 v37, 0, v36
	v_mul_f32_e64 v36, |v36|, s35
	v_exp_f32_e32 v36, v36
	s_nop 0
	v_add_f32_e32 v36, 1.0, v36
	v_cmp_gt_f32_e32 vcc, s33, v36
	s_nop 1
	v_cndmask_b32_e64 v38, 0, 32, vcc
	v_ldexp_f32 v36, v36, v38
	v_log_f32_e32 v36, v36
	s_nop 0
	v_mul_f32_e32 v38, 0x3f317217, v36
	v_fma_f32 v38, v36, s36, -v38
	v_fmac_f32_e32 v38, 0x3377d1cf, v36
	v_fmac_f32_e32 v38, 0x3f317217, v36
	v_cmp_lt_f32_e64 s[12:13], |v36|, s37
	s_nop 1
	v_cndmask_b32_e64 v36, v36, v38, s[12:13]
	v_cndmask_b32_e32 v38, 0, v179, vcc
	v_sub_f32_e32 v36, v36, v38
	ds_read_b128 v[38:41], v43 offset:128
	v_sub_f32_e32 v36, v37, v36
	v_fmamk_f32 v36, v36, 0x3d800000, v34
	s_waitcnt lgkmcnt(0)
	v_fma_f32 v37, v30, v38, v35
	v_fmac_f32_e32 v37, v31, v39
	v_fmac_f32_e32 v37, v32, v40
	v_fmac_f32_e32 v37, v33, v41
	ds_read_b128 v[38:41], v43 offset:144
	s_waitcnt lgkmcnt(0)
	v_fmac_f32_e32 v37, v26, v38
	v_fmac_f32_e32 v37, v27, v39
	v_fmac_f32_e32 v37, v28, v40
	v_fmac_f32_e32 v37, v29, v41
	ds_read_b128 v[38:41], v43 offset:160
	s_waitcnt lgkmcnt(0)
	v_fmac_f32_e32 v37, v22, v38
	v_fmac_f32_e32 v37, v23, v39
	v_fmac_f32_e32 v37, v24, v40
	v_fmac_f32_e32 v37, v25, v41
	ds_read_b128 v[38:41], v43 offset:176
	s_waitcnt lgkmcnt(0)
	v_pk_mul_f32 v[38:39], v[0:1], v[38:39]
	s_nop 0
	v_add_f32_e32 v37, v37, v38
	v_add_f32_e32 v37, v37, v39
	v_pk_mul_f32 v[38:39], v[2:3], v[40:41]
	s_nop 0
	v_add_f32_e32 v37, v37, v38
	v_add_f32_e32 v37, v37, v39
	v_min_f32_e32 v38, 0, v37
	v_mul_f32_e64 v37, |v37|, s35
	v_exp_f32_e32 v37, v37
	s_nop 0
	v_add_f32_e32 v37, 1.0, v37
	v_cmp_gt_f32_e32 vcc, s33, v37
	s_nop 1
	v_cndmask_b32_e64 v39, 0, 32, vcc
	v_ldexp_f32 v37, v37, v39
	v_log_f32_e32 v37, v37
	s_nop 0
	v_mul_f32_e32 v39, 0x3f317217, v37
	v_fma_f32 v39, v37, s36, -v39
	v_fmac_f32_e32 v39, 0x3377d1cf, v37
	v_fmac_f32_e32 v39, 0x3f317217, v37
	v_cmp_lt_f32_e64 s[12:13], |v37|, s37
	s_nop 1
	v_cndmask_b32_e64 v37, v37, v39, s[12:13]
	v_cndmask_b32_e32 v39, 0, v179, vcc
	v_sub_f32_e32 v37, v37, v39
	v_sub_f32_e32 v37, v38, v37
	ds_read_b128 v[38:41], v43 offset:192
	v_fmamk_f32 v37, v37, 0x3d800000, v36
	s_waitcnt lgkmcnt(0)
	v_fma_f32 v49, v30, v38, v35
	v_fmac_f32_e32 v49, v31, v39
	v_fmac_f32_e32 v49, v32, v40
	v_fmac_f32_e32 v49, v33, v41
	ds_read_b128 v[38:41], v43 offset:208
	s_waitcnt lgkmcnt(0)
	v_fmac_f32_e32 v49, v26, v38
	v_fmac_f32_e32 v49, v27, v39
	v_fmac_f32_e32 v49, v28, v40
	v_fmac_f32_e32 v49, v29, v41
	ds_read_b128 v[38:41], v43 offset:224
	s_waitcnt lgkmcnt(0)
	v_fmac_f32_e32 v49, v22, v38
	v_fmac_f32_e32 v49, v23, v39
	v_fmac_f32_e32 v49, v24, v40
	v_fmac_f32_e32 v49, v25, v41
	ds_read_b128 v[38:41], v43 offset:240
	s_waitcnt lgkmcnt(0)
	v_pk_mul_f32 v[38:39], v[0:1], v[38:39]
	s_nop 0
	v_add_f32_e32 v38, v49, v38
	v_add_f32_e32 v49, v38, v39
	v_pk_mul_f32 v[38:39], v[2:3], v[40:41]
	s_nop 0
	v_add_f32_e32 v38, v49, v38
	v_add_f32_e32 v38, v38, v39
	v_min_f32_e32 v39, 0, v38
	v_mul_f32_e64 v38, |v38|, s35
	v_exp_f32_e32 v38, v38
	s_nop 0
	v_add_f32_e32 v38, 1.0, v38
	v_cmp_gt_f32_e32 vcc, s33, v38
	s_nop 1
	v_cndmask_b32_e64 v40, 0, 32, vcc
	v_ldexp_f32 v38, v38, v40
	v_log_f32_e32 v38, v38
	s_nop 0
	v_mul_f32_e32 v40, 0x3f317217, v38
	v_fma_f32 v40, v38, s36, -v40
	v_fmac_f32_e32 v40, 0x3377d1cf, v38
	v_fmac_f32_e32 v40, 0x3f317217, v38
	v_cmp_lt_f32_e64 s[12:13], |v38|, s37
	s_nop 1
	v_cndmask_b32_e64 v38, v38, v40, s[12:13]
	v_cndmask_b32_e32 v40, 0, v179, vcc
	v_sub_f32_e32 v38, v38, v40
	v_sub_f32_e32 v38, v39, v38
	v_fma_f32 v39, v30, v50, v35
	v_fmac_f32_e32 v39, v31, v51
	v_fmac_f32_e32 v39, v32, v52
	v_fmac_f32_e32 v39, v33, v53
	ds_read_b128 v[50:53], v43 offset:272
	v_fmamk_f32 v38, v38, 0x3d800000, v37
	s_waitcnt lgkmcnt(0)
	v_fmac_f32_e32 v39, v26, v50
	v_fmac_f32_e32 v39, v27, v51
	v_fmac_f32_e32 v39, v28, v52
	v_fmac_f32_e32 v39, v29, v53
	ds_read_b128 v[50:53], v43 offset:288
	s_waitcnt lgkmcnt(0)
	v_fmac_f32_e32 v39, v22, v50
	v_fmac_f32_e32 v39, v23, v51
	v_fmac_f32_e32 v39, v24, v52
	v_fmac_f32_e32 v39, v25, v53
	ds_read_b128 v[50:53], v43 offset:304
	s_waitcnt lgkmcnt(0)
	v_pk_mul_f32 v[40:41], v[0:1], v[50:51]
	s_nop 0
	v_add_f32_e32 v39, v39, v40
	v_add_f32_e32 v39, v39, v41
	v_pk_mul_f32 v[40:41], v[2:3], v[52:53]
	ds_read_b128 v[50:53], v43 offset:320
	v_add_f32_e32 v39, v39, v40
	v_add_f32_e32 v39, v39, v41
	v_min_f32_e32 v40, 0, v39
	v_mul_f32_e64 v39, |v39|, s35
	s_waitcnt lgkmcnt(0)
	v_fma_f32 v49, v30, v50, v35
	v_fmac_f32_e32 v49, v31, v51
	v_fmac_f32_e32 v49, v32, v52
	v_fmac_f32_e32 v49, v33, v53
	ds_read_b128 v[50:53], v43 offset:336
	v_exp_f32_e32 v39, v39
	s_waitcnt lgkmcnt(0)
	v_fmac_f32_e32 v49, v26, v50
	v_fmac_f32_e32 v49, v27, v51
	v_add_f32_e32 v39, 1.0, v39
	v_fmac_f32_e32 v49, v28, v52
	v_cmp_gt_f32_e32 vcc, s33, v39
	v_fmac_f32_e32 v49, v29, v53
	ds_read_b128 v[50:53], v43 offset:352
	v_cndmask_b32_e64 v41, 0, 32, vcc
	v_ldexp_f32 v39, v39, v41
	v_log_f32_e32 v39, v39
	s_waitcnt lgkmcnt(0)
	v_fmac_f32_e32 v49, v22, v50
	v_fmac_f32_e32 v49, v23, v51
	v_mul_f32_e32 v41, 0x3f317217, v39
	v_fmac_f32_e32 v49, v24, v52
	v_fma_f32 v41, v39, s36, -v41
	v_fmac_f32_e32 v49, v25, v53
	ds_read_b128 v[50:53], v43 offset:368
	v_fmac_f32_e32 v41, 0x3377d1cf, v39
	v_fmac_f32_e32 v41, 0x3f317217, v39
	v_cmp_lt_f32_e64 s[12:13], |v39|, s37
	s_nop 1
	v_cndmask_b32_e64 v39, v39, v41, s[12:13]
	v_cndmask_b32_e32 v41, 0, v179, vcc
	v_sub_f32_e32 v39, v39, v41
	v_sub_f32_e32 v39, v40, v39
	s_waitcnt lgkmcnt(0)
	v_pk_mul_f32 v[40:41], v[0:1], v[50:51]
	v_fmamk_f32 v39, v39, 0x3d800000, v38
	v_add_f32_e32 v40, v49, v40
	v_add_f32_e32 v49, v40, v41
	v_pk_mul_f32 v[40:41], v[2:3], v[52:53]
	ds_read_b128 v[50:53], v43 offset:384
	v_add_f32_e32 v40, v49, v40
	v_add_f32_e32 v40, v40, v41
	v_min_f32_e32 v41, 0, v40
	v_mul_f32_e64 v40, |v40|, s35
	v_exp_f32_e32 v40, v40
	s_nop 0
	v_add_f32_e32 v40, 1.0, v40
	v_cmp_gt_f32_e32 vcc, s33, v40
	s_nop 1
	v_cndmask_b32_e64 v49, 0, 32, vcc
	v_ldexp_f32 v40, v40, v49
	v_log_f32_e32 v40, v40
	s_nop 0
	v_mul_f32_e32 v49, 0x3f317217, v40
	v_fma_f32 v49, v40, s36, -v49
	v_fmac_f32_e32 v49, 0x3377d1cf, v40
	v_fmac_f32_e32 v49, 0x3f317217, v40
	v_cmp_lt_f32_e64 s[12:13], |v40|, s37
	s_nop 1
	v_cndmask_b32_e64 v40, v40, v49, s[12:13]
	v_cndmask_b32_e32 v49, 0, v179, vcc
	v_sub_f32_e32 v40, v40, v49
	v_sub_f32_e32 v40, v41, v40
	v_fmamk_f32 v41, v40, 0x3d800000, v39
	s_waitcnt lgkmcnt(0)
	v_fma_f32 v40, v30, v50, v35
	v_fmac_f32_e32 v40, v31, v51
	v_fmac_f32_e32 v40, v32, v52
	v_fmac_f32_e32 v40, v33, v53
	ds_read_b128 v[50:53], v43 offset:400
	s_waitcnt lgkmcnt(0)
	v_fmac_f32_e32 v40, v26, v50
	v_fmac_f32_e32 v40, v27, v51
	v_fmac_f32_e32 v40, v28, v52
	v_fmac_f32_e32 v40, v29, v53
	ds_read_b128 v[50:53], v43 offset:416
	s_waitcnt lgkmcnt(0)
	v_fmac_f32_e32 v40, v22, v50
	v_fmac_f32_e32 v40, v23, v51
	v_fmac_f32_e32 v40, v24, v52
	v_fmac_f32_e32 v40, v25, v53
	ds_read_b128 v[50:53], v43 offset:432
	s_waitcnt lgkmcnt(0)
	v_pk_mul_f32 v[50:51], v[0:1], v[50:51]
	s_nop 0
	v_add_f32_e32 v40, v40, v50
	v_add_f32_e32 v40, v40, v51
	v_pk_mul_f32 v[50:51], v[2:3], v[52:53]
	s_nop 0
	v_add_f32_e32 v40, v40, v50
	v_add_f32_e32 v40, v40, v51
	v_min_f32_e32 v49, 0, v40
	v_mul_f32_e64 v40, |v40|, s35
	v_exp_f32_e32 v40, v40
	s_nop 0
	v_add_f32_e32 v40, 1.0, v40
	v_cmp_gt_f32_e32 vcc, s33, v40
	s_nop 1
	v_cndmask_b32_e64 v50, 0, 32, vcc
	v_ldexp_f32 v40, v40, v50
	v_log_f32_e32 v40, v40
	s_nop 0
	v_mul_f32_e32 v50, 0x3f317217, v40
	v_fma_f32 v50, v40, s36, -v50
	v_fmac_f32_e32 v50, 0x3377d1cf, v40
	v_fmac_f32_e32 v50, 0x3f317217, v40
	v_cmp_lt_f32_e64 s[12:13], |v40|, s37
	s_nop 1
	v_cndmask_b32_e64 v40, v40, v50, s[12:13]
	v_cndmask_b32_e32 v50, 0, v179, vcc
	v_sub_f32_e32 v40, v40, v50
	ds_read_b128 v[50:53], v43 offset:448
	v_sub_f32_e32 v40, v49, v40
	v_fmamk_f32 v49, v40, 0x3d800000, v41
	s_waitcnt lgkmcnt(0)
	v_fma_f32 v40, v30, v50, v35
	v_fmac_f32_e32 v40, v31, v51
	v_fmac_f32_e32 v40, v32, v52
	v_fmac_f32_e32 v40, v33, v53
	ds_read_b128 v[50:53], v43 offset:464
	s_waitcnt lgkmcnt(0)
	v_fmac_f32_e32 v40, v26, v50
	v_fmac_f32_e32 v40, v27, v51
	v_fmac_f32_e32 v40, v28, v52
	v_fmac_f32_e32 v40, v29, v53
	ds_read_b128 v[50:53], v43 offset:480
	s_waitcnt lgkmcnt(0)
	v_fmac_f32_e32 v40, v22, v50
	v_fmac_f32_e32 v40, v23, v51
	v_fmac_f32_e32 v40, v24, v52
	v_fmac_f32_e32 v40, v25, v53
	ds_read_b128 v[50:53], v43 offset:496
	s_waitcnt lgkmcnt(0)
	v_pk_mul_f32 v[50:51], v[0:1], v[50:51]
	s_nop 0
	v_add_f32_e32 v40, v40, v50
	v_add_f32_e32 v40, v40, v51
	v_pk_mul_f32 v[50:51], v[2:3], v[52:53]
	ds_read_b128 v[52:55], v43 offset:512
	v_add_f32_e32 v40, v40, v50
	v_add_f32_e32 v40, v40, v51
	v_min_f32_e32 v50, 0, v40
	v_mul_f32_e64 v40, |v40|, s35
	v_exp_f32_e32 v40, v40
	s_nop 0
	v_add_f32_e32 v40, 1.0, v40
	v_cmp_gt_f32_e32 vcc, s33, v40
	s_nop 1
	v_cndmask_b32_e64 v51, 0, 32, vcc
	v_ldexp_f32 v40, v40, v51
	v_log_f32_e32 v40, v40
	s_nop 0
	v_mul_f32_e32 v51, 0x3f317217, v40
	v_fma_f32 v51, v40, s36, -v51
	v_fmac_f32_e32 v51, 0x3377d1cf, v40
	v_fmac_f32_e32 v51, 0x3f317217, v40
	v_cmp_lt_f32_e64 s[12:13], |v40|, s37
	s_nop 1
	v_cndmask_b32_e64 v40, v40, v51, s[12:13]
	v_cndmask_b32_e32 v51, 0, v179, vcc
	v_sub_f32_e32 v40, v40, v51
	v_sub_f32_e32 v40, v50, v40
	v_fmamk_f32 v51, v40, 0x3d800000, v49
	s_waitcnt lgkmcnt(0)
	v_fma_f32 v40, v30, v52, v35
	v_fmac_f32_e32 v40, v31, v53
	v_fmac_f32_e32 v40, v32, v54
	v_fmac_f32_e32 v40, v33, v55
	ds_read_b128 v[52:55], v43 offset:528
	s_waitcnt lgkmcnt(0)
	v_fmac_f32_e32 v40, v26, v52
	v_fmac_f32_e32 v40, v27, v53
	v_fmac_f32_e32 v40, v28, v54
	v_fmac_f32_e32 v40, v29, v55
	ds_read_b128 v[52:55], v43 offset:544
	s_waitcnt lgkmcnt(0)
	v_fmac_f32_e32 v40, v22, v52
	v_fmac_f32_e32 v40, v23, v53
	v_fmac_f32_e32 v40, v24, v54
	v_fmac_f32_e32 v40, v25, v55
	ds_read_b128 v[52:55], v43 offset:560
	s_waitcnt lgkmcnt(0)
	v_pk_mul_f32 v[52:53], v[0:1], v[52:53]
	s_nop 0
	v_add_f32_e32 v40, v40, v52
	v_add_f32_e32 v40, v40, v53
	v_pk_mul_f32 v[52:53], v[2:3], v[54:55]
	s_nop 0
	v_add_f32_e32 v40, v40, v52
	v_add_f32_e32 v40, v40, v53
	v_min_f32_e32 v50, 0, v40
	v_mul_f32_e64 v40, |v40|, s35
	v_exp_f32_e32 v40, v40
	s_nop 0
	v_add_f32_e32 v40, 1.0, v40
	v_cmp_gt_f32_e32 vcc, s33, v40
	s_nop 1
	v_cndmask_b32_e64 v52, 0, 32, vcc
	v_ldexp_f32 v40, v40, v52
	v_log_f32_e32 v40, v40
	s_nop 0
	v_mul_f32_e32 v52, 0x3f317217, v40
	v_fma_f32 v52, v40, s36, -v52
	v_fmac_f32_e32 v52, 0x3377d1cf, v40
	v_fmac_f32_e32 v52, 0x3f317217, v40
	v_cmp_lt_f32_e64 s[12:13], |v40|, s37
	s_nop 1
	v_cndmask_b32_e64 v40, v40, v52, s[12:13]
	v_cndmask_b32_e32 v52, 0, v179, vcc
	v_sub_f32_e32 v40, v40, v52
	ds_read_b128 v[52:55], v43 offset:576
	v_sub_f32_e32 v40, v50, v40
	v_fmamk_f32 v40, v40, 0x3d800000, v51
	s_waitcnt lgkmcnt(0)
	v_fma_f32 v50, v30, v52, v35
	v_fmac_f32_e32 v50, v31, v53
	v_fmac_f32_e32 v50, v32, v54
	v_fmac_f32_e32 v50, v33, v55
	ds_read_b128 v[52:55], v43 offset:592
	s_waitcnt lgkmcnt(0)
	v_fmac_f32_e32 v50, v26, v52
	v_fmac_f32_e32 v50, v27, v53
	v_fmac_f32_e32 v50, v28, v54
	v_fmac_f32_e32 v50, v29, v55
	ds_read_b128 v[52:55], v43 offset:608
	s_waitcnt lgkmcnt(0)
	v_fmac_f32_e32 v50, v22, v52
	v_fmac_f32_e32 v50, v23, v53
	v_fmac_f32_e32 v50, v24, v54
	v_fmac_f32_e32 v50, v25, v55
	ds_read_b128 v[52:55], v43 offset:624
	s_waitcnt lgkmcnt(0)
	v_pk_mul_f32 v[52:53], v[0:1], v[52:53]
	s_nop 0
	v_add_f32_e32 v50, v50, v52
	v_add_f32_e32 v50, v50, v53
	v_pk_mul_f32 v[52:53], v[2:3], v[54:55]
	s_nop 0
	v_add_f32_e32 v50, v50, v52
	v_add_f32_e32 v50, v50, v53
	v_min_f32_e32 v52, 0, v50
	v_mul_f32_e64 v50, |v50|, s35
	v_exp_f32_e32 v50, v50
	s_nop 0
	v_add_f32_e32 v50, 1.0, v50
	v_cmp_gt_f32_e32 vcc, s33, v50
	s_nop 1
	v_cndmask_b32_e64 v53, 0, 32, vcc
	v_ldexp_f32 v50, v50, v53
	v_log_f32_e32 v50, v50
	s_nop 0
	v_mul_f32_e32 v53, 0x3f317217, v50
	v_fma_f32 v53, v50, s36, -v53
	v_fmac_f32_e32 v53, 0x3377d1cf, v50
	v_fmac_f32_e32 v53, 0x3f317217, v50
	v_cmp_lt_f32_e64 s[12:13], |v50|, s37
	s_nop 1
	v_cndmask_b32_e64 v50, v50, v53, s[12:13]
	v_cndmask_b32_e32 v53, 0, v179, vcc
	v_sub_f32_e32 v50, v50, v53
	v_sub_f32_e32 v50, v52, v50
	ds_read_b128 v[52:55], v43 offset:640
	v_fmamk_f32 v50, v50, 0x3d800000, v40
	s_waitcnt lgkmcnt(0)
	v_fma_f32 v56, v30, v52, v35
	v_fmac_f32_e32 v56, v31, v53
	v_fmac_f32_e32 v56, v32, v54
	v_fmac_f32_e32 v56, v33, v55
	ds_read_b128 v[52:55], v43 offset:656
	s_waitcnt lgkmcnt(0)
	v_fmac_f32_e32 v56, v26, v52
	v_fmac_f32_e32 v56, v27, v53
	v_fmac_f32_e32 v56, v28, v54
	v_fmac_f32_e32 v56, v29, v55
	ds_read_b128 v[52:55], v43 offset:672
	s_waitcnt lgkmcnt(0)
	v_fmac_f32_e32 v56, v22, v52
	v_fmac_f32_e32 v56, v23, v53
	v_fmac_f32_e32 v56, v24, v54
	v_fmac_f32_e32 v56, v25, v55
	ds_read_b128 v[52:55], v43 offset:688
	s_waitcnt lgkmcnt(0)
	v_pk_mul_f32 v[52:53], v[0:1], v[52:53]
	s_nop 0
	v_add_f32_e32 v52, v56, v52
	v_add_f32_e32 v56, v52, v53
	v_pk_mul_f32 v[52:53], v[2:3], v[54:55]
	s_nop 0
	v_add_f32_e32 v52, v56, v52
	v_add_f32_e32 v52, v52, v53
	v_min_f32_e32 v53, 0, v52
	v_mul_f32_e64 v52, |v52|, s35
	v_exp_f32_e32 v52, v52
	s_nop 0
	v_add_f32_e32 v52, 1.0, v52
	v_cmp_gt_f32_e32 vcc, s33, v52
	s_nop 1
	v_cndmask_b32_e64 v54, 0, 32, vcc
	v_ldexp_f32 v52, v52, v54
	v_log_f32_e32 v52, v52
	s_nop 0
	v_mul_f32_e32 v54, 0x3f317217, v52
	v_fma_f32 v54, v52, s36, -v54
	v_fmac_f32_e32 v54, 0x3377d1cf, v52
	v_fmac_f32_e32 v54, 0x3f317217, v52
	v_cmp_lt_f32_e64 s[12:13], |v52|, s37
	s_nop 1
	v_cndmask_b32_e64 v52, v52, v54, s[12:13]
	v_cndmask_b32_e32 v54, 0, v179, vcc
	v_sub_f32_e32 v52, v52, v54
	ds_read_b128 v[54:57], v43 offset:704
	v_sub_f32_e32 v52, v53, v52
	v_fmamk_f32 v52, v52, 0x3d800000, v50
	s_waitcnt lgkmcnt(0)
	v_fma_f32 v53, v30, v54, v35
	v_fmac_f32_e32 v53, v31, v55
	v_fmac_f32_e32 v53, v32, v56
	v_fmac_f32_e32 v53, v33, v57
	ds_read_b128 v[54:57], v43 offset:720
	s_waitcnt lgkmcnt(0)
	v_fmac_f32_e32 v53, v26, v54
	v_fmac_f32_e32 v53, v27, v55
	v_fmac_f32_e32 v53, v28, v56
	v_fmac_f32_e32 v53, v29, v57
	ds_read_b128 v[54:57], v43 offset:736
	s_waitcnt lgkmcnt(0)
	v_fmac_f32_e32 v53, v22, v54
	v_fmac_f32_e32 v53, v23, v55
	v_fmac_f32_e32 v53, v24, v56
	v_fmac_f32_e32 v53, v25, v57
	ds_read_b128 v[54:57], v43 offset:752
	s_waitcnt lgkmcnt(0)
	v_pk_mul_f32 v[54:55], v[0:1], v[54:55]
	s_nop 0
	v_add_f32_e32 v53, v53, v54
	v_add_f32_e32 v53, v53, v55
	v_pk_mul_f32 v[54:55], v[2:3], v[56:57]
	s_nop 0
	v_add_f32_e32 v53, v53, v54
	v_add_f32_e32 v53, v53, v55
	v_min_f32_e32 v54, 0, v53
	v_mul_f32_e64 v53, |v53|, s35
	v_exp_f32_e32 v53, v53
	s_nop 0
	v_add_f32_e32 v53, 1.0, v53
	v_cmp_gt_f32_e32 vcc, s33, v53
	s_nop 1
	v_cndmask_b32_e64 v55, 0, 32, vcc
	v_ldexp_f32 v53, v53, v55
	v_log_f32_e32 v53, v53
	s_nop 0
	v_mul_f32_e32 v55, 0x3f317217, v53
	v_fma_f32 v55, v53, s36, -v55
	v_fmac_f32_e32 v55, 0x3377d1cf, v53
	v_fmac_f32_e32 v55, 0x3f317217, v53
	v_cmp_lt_f32_e64 s[12:13], |v53|, s37
	s_nop 1
	v_cndmask_b32_e64 v53, v53, v55, s[12:13]
	v_cndmask_b32_e32 v55, 0, v179, vcc
	v_sub_f32_e32 v53, v53, v55
	v_sub_f32_e32 v53, v54, v53
	ds_read_b128 v[54:57], v43 offset:768
	v_fmamk_f32 v53, v53, 0x3d800000, v52
	s_waitcnt lgkmcnt(0)
	v_fma_f32 v58, v30, v54, v35
	v_fmac_f32_e32 v58, v31, v55
	v_fmac_f32_e32 v58, v32, v56
	v_fmac_f32_e32 v58, v33, v57
	ds_read_b128 v[54:57], v43 offset:784
	s_waitcnt lgkmcnt(0)
	v_fmac_f32_e32 v58, v26, v54
	v_fmac_f32_e32 v58, v27, v55
	v_fmac_f32_e32 v58, v28, v56
	v_fmac_f32_e32 v58, v29, v57
	ds_read_b128 v[54:57], v43 offset:800
	s_waitcnt lgkmcnt(0)
	v_fmac_f32_e32 v58, v22, v54
	v_fmac_f32_e32 v58, v23, v55
	v_fmac_f32_e32 v58, v24, v56
	v_fmac_f32_e32 v58, v25, v57
	ds_read_b128 v[54:57], v43 offset:816
	s_waitcnt lgkmcnt(0)
	v_pk_mul_f32 v[54:55], v[0:1], v[54:55]
	s_nop 0
	v_add_f32_e32 v54, v58, v54
	v_add_f32_e32 v58, v54, v55
	v_pk_mul_f32 v[54:55], v[2:3], v[56:57]
	s_nop 0
	v_add_f32_e32 v54, v58, v54
	v_add_f32_e32 v54, v54, v55
	v_min_f32_e32 v55, 0, v54
	v_mul_f32_e64 v54, |v54|, s35
	v_exp_f32_e32 v54, v54
	s_nop 0
	v_add_f32_e32 v54, 1.0, v54
	v_cmp_gt_f32_e32 vcc, s33, v54
	s_nop 1
	v_cndmask_b32_e64 v56, 0, 32, vcc
	v_ldexp_f32 v54, v54, v56
	v_log_f32_e32 v54, v54
	s_nop 0
	v_mul_f32_e32 v56, 0x3f317217, v54
	v_fma_f32 v56, v54, s36, -v56
	v_fmac_f32_e32 v56, 0x3377d1cf, v54
	v_fmac_f32_e32 v56, 0x3f317217, v54
	v_cmp_lt_f32_e64 s[12:13], |v54|, s37
	s_nop 1
	v_cndmask_b32_e64 v54, v54, v56, s[12:13]
	v_cndmask_b32_e32 v56, 0, v179, vcc
	v_sub_f32_e32 v54, v54, v56
	ds_read_b128 v[56:59], v43 offset:832
	v_sub_f32_e32 v54, v55, v54
	v_fmamk_f32 v54, v54, 0x3d800000, v53
	s_waitcnt lgkmcnt(0)
	v_fma_f32 v55, v30, v56, v35
	v_fmac_f32_e32 v55, v31, v57
	v_fmac_f32_e32 v55, v32, v58
	v_fmac_f32_e32 v55, v33, v59
	ds_read_b128 v[56:59], v43 offset:848
	s_waitcnt lgkmcnt(0)
	v_fmac_f32_e32 v55, v26, v56
	v_fmac_f32_e32 v55, v27, v57
	v_fmac_f32_e32 v55, v28, v58
	v_fmac_f32_e32 v55, v29, v59
	ds_read_b128 v[56:59], v43 offset:864
	s_waitcnt lgkmcnt(0)
	v_fmac_f32_e32 v55, v22, v56
	v_fmac_f32_e32 v55, v23, v57
	v_pk_mul_f32 v[56:57], v[24:25], v[58:59]
	s_nop 0
	v_add_f32_e32 v55, v55, v56
	v_add_f32_e32 v55, v55, v57
	ds_read_b128 v[56:59], v43 offset:880
	s_waitcnt lgkmcnt(0)
	v_pk_mul_f32 v[56:57], v[0:1], v[56:57]
	s_nop 0
	v_add_f32_e32 v55, v55, v56
	v_add_f32_e32 v55, v55, v57
	v_pk_mul_f32 v[56:57], v[2:3], v[58:59]
	s_nop 0
	v_add_f32_e32 v55, v55, v56
	v_add_f32_e32 v55, v55, v57
	v_min_f32_e32 v56, 0, v55
	v_mul_f32_e64 v55, |v55|, s35
	v_exp_f32_e32 v55, v55
	s_nop 0
	v_add_f32_e32 v55, 1.0, v55
	v_cmp_gt_f32_e32 vcc, s33, v55
	s_nop 1
	v_cndmask_b32_e64 v57, 0, 32, vcc
	v_ldexp_f32 v55, v55, v57
	v_log_f32_e32 v55, v55
	s_nop 0
	v_mul_f32_e32 v57, 0x3f317217, v55
	v_fma_f32 v57, v55, s36, -v57
	v_fmac_f32_e32 v57, 0x3377d1cf, v55
	v_fmac_f32_e32 v57, 0x3f317217, v55
	v_cmp_lt_f32_e64 s[12:13], |v55|, s37
	s_nop 1
	v_cndmask_b32_e64 v55, v55, v57, s[12:13]
	v_cndmask_b32_e32 v57, 0, v179, vcc
	v_sub_f32_e32 v55, v55, v57
	v_sub_f32_e32 v55, v56, v55
	ds_read_b128 v[56:59], v43 offset:896
	v_fmamk_f32 v55, v55, 0x3d800000, v54
	s_waitcnt lgkmcnt(0)
	v_fma_f32 v60, v30, v56, v35
	v_fmac_f32_e32 v60, v31, v57
	v_fmac_f32_e32 v60, v32, v58
	v_fmac_f32_e32 v60, v33, v59
	ds_read_b128 v[56:59], v43 offset:912
	s_waitcnt lgkmcnt(0)
	v_fmac_f32_e32 v60, v26, v56
	v_fmac_f32_e32 v60, v27, v57
	v_fmac_f32_e32 v60, v28, v58
	v_fmac_f32_e32 v60, v29, v59
	ds_read_b128 v[56:59], v43 offset:928
	s_waitcnt lgkmcnt(0)
	v_fmac_f32_e32 v60, v22, v56
	v_fmac_f32_e32 v60, v23, v57
	v_pk_mul_f32 v[56:57], v[24:25], v[58:59]
	s_nop 0
	v_add_f32_e32 v56, v60, v56
	v_add_f32_e32 v60, v56, v57
	ds_read_b128 v[56:59], v43 offset:944
	s_waitcnt lgkmcnt(0)
	v_pk_mul_f32 v[56:57], v[0:1], v[56:57]
	s_nop 0
	v_add_f32_e32 v56, v60, v56
	v_add_f32_e32 v60, v56, v57
	v_pk_mul_f32 v[56:57], v[2:3], v[58:59]
	s_nop 0
	v_add_f32_e32 v56, v60, v56
	v_add_f32_e32 v56, v56, v57
	v_min_f32_e32 v57, 0, v56
	v_mul_f32_e64 v56, |v56|, s35
	v_exp_f32_e32 v56, v56
	s_nop 0
	v_add_f32_e32 v56, 1.0, v56
	v_cmp_gt_f32_e32 vcc, s33, v56
	s_nop 1
	v_cndmask_b32_e64 v58, 0, 32, vcc
	v_ldexp_f32 v56, v56, v58
	v_log_f32_e32 v56, v56
	s_nop 0
	v_mul_f32_e32 v58, 0x3f317217, v56
	v_fma_f32 v58, v56, s36, -v58
	v_fmac_f32_e32 v58, 0x3377d1cf, v56
	v_fmac_f32_e32 v58, 0x3f317217, v56
	v_cmp_lt_f32_e64 s[12:13], |v56|, s37
	s_nop 1
	v_cndmask_b32_e64 v56, v56, v58, s[12:13]
	v_cndmask_b32_e32 v58, 0, v179, vcc
	v_sub_f32_e32 v56, v56, v58
	ds_read_b128 v[58:61], v43 offset:960
	v_sub_f32_e32 v56, v57, v56
	v_fmamk_f32 v56, v56, 0x3d800000, v55
	s_waitcnt lgkmcnt(0)
	v_fmac_f32_e32 v35, v30, v58
	v_fmac_f32_e32 v35, v31, v59
	v_fmac_f32_e32 v35, v32, v60
	v_fmac_f32_e32 v35, v33, v61
	ds_read_b128 v[30:33], v43 offset:976
	s_waitcnt lgkmcnt(0)
	v_fmac_f32_e32 v35, v26, v30
	v_fmac_f32_e32 v35, v27, v31
	v_fmac_f32_e32 v35, v28, v32
	v_fmac_f32_e32 v35, v29, v33
	ds_read_b128 v[26:29], v43 offset:992
	s_waitcnt lgkmcnt(0)
	v_pk_mul_f32 v[22:23], v[22:23], v[26:27]
	s_nop 0
	v_add_f32_e32 v22, v35, v22
	v_add_f32_e32 v26, v22, v23
	v_pk_mul_f32 v[22:23], v[24:25], v[28:29]
	s_nop 0
	v_add_f32_e32 v22, v26, v22
	v_add_f32_e32 v26, v22, v23
	ds_read_b128 v[22:25], v43 offset:1008
	s_waitcnt lgkmcnt(0)
	v_pk_mul_f32 v[0:1], v[0:1], v[22:23]
	s_nop 0
	v_add_f32_e32 v0, v26, v0
	v_add_f32_e32 v22, v0, v1
	v_pk_mul_f32 v[0:1], v[2:3], v[24:25]
	s_nop 0
	v_add_f32_e32 v0, v22, v0
	v_add_f32_e32 v0, v0, v1
	v_min_f32_e32 v1, 0, v0
	v_mul_f32_e64 v0, |v0|, s35
	v_exp_f32_e32 v0, v0
	s_nop 0
	v_add_f32_e32 v0, 1.0, v0
	v_cmp_gt_f32_e32 vcc, s33, v0
	s_nop 1
	v_cndmask_b32_e64 v2, 0, 32, vcc
	v_ldexp_f32 v0, v0, v2
	v_log_f32_e32 v0, v0
	s_nop 0
	v_mul_f32_e32 v2, 0x3f317217, v0
	v_fma_f32 v2, v0, s36, -v2
	v_fmac_f32_e32 v2, 0x3377d1cf, v0
	v_fmac_f32_e32 v2, 0x3f317217, v0
	v_cmp_lt_f32_e64 s[12:13], |v0|, s37
	s_nop 1
	v_cndmask_b32_e64 v0, v0, v2, s[12:13]
	v_cndmask_b32_e32 v2, 0, v179, vcc
	v_sub_f32_e32 v0, v0, v2
	v_sub_f32_e32 v0, v1, v0
	v_fmamk_f32 v3, v0, 0x3d800000, v56
	ds_write_b32 v44, v3 offset:4096
	s_waitcnt lgkmcnt(0)
	s_barrier
	ds_read2st64_b32 v[0:1], v45 offset0:16 offset1:18
	ds_read2st64_b32 v[22:23], v45 offset0:20 offset1:22
	s_mov_b64 s[12:13], -1
	s_waitcnt lgkmcnt(1)
	v_add_f32_e32 v0, 0, v0
	v_cndmask_b32_e64 v2, 0, v0, s[4:5]
	v_add_f32_e32 v0, v0, v1
	v_add_f32_e32 v1, v1, v2
	v_cndmask_b32_e64 v1, v2, v1, s[6:7]
	s_waitcnt lgkmcnt(0)
	v_add_f32_e32 v2, v0, v22
	v_add_f32_e32 v0, v22, v1
	v_cndmask_b32_e64 v0, v1, v0, s[18:19]
	v_add_f32_e32 v1, v23, v0
	v_cndmask_b32_e64 v1, v0, v1, s[20:21]
	v_add_f32_e32 v24, v34, v1
	ds_read_u16 v0, v10 offset:8192
	v_mul_f32_e32 v22, 0x3fb8aa3b, v24
	v_exp_f32_e32 v22, v22
	s_waitcnt lgkmcnt(0)
	v_lshlrev_b32_e32 v0, 16, v0
	v_mul_f32_e32 v0, v22, v0
	v_cvt_pk_bf16_f32 v0, v0, s0
	ds_write_b16 v10, v0 offset:43008
	v_mul_f32_e32 v0, 0xbfb8aa3b, v24
	v_exp_f32_e32 v25, v0
	v_mov_b32_e32 v0, v23
	v_pk_add_f32 v[22:23], v[2:3], v[0:1]
	ds_read_u16 v3, v10 offset:8464
	v_sub_f32_e32 v0, v22, v24
	v_mul_f32_e32 v0, 0x3fb8aa3b, v0
	v_exp_f32_e32 v2, v0
	v_add_f32_e32 v0, v36, v1
	v_mul_f32_e32 v24, 0x3fb8aa3b, v0
	v_exp_f32_e32 v24, v24
	s_waitcnt lgkmcnt(0)
	v_lshlrev_b32_e32 v3, 16, v3
	v_mul_f32_e32 v3, v24, v3
	v_cvt_pk_bf16_f32 v3, v3, s0
	ds_write_b16 v10, v3 offset:43280
	v_mul_f32_e32 v3, 0xbfb8aa3b, v0
	v_sub_f32_e32 v0, v22, v0
	v_mul_f32_e32 v0, 0x3fb8aa3b, v0
	v_exp_f32_e32 v28, v3
	v_exp_f32_e32 v3, v0
	ds_read_u16 v0, v10 offset:25600
	ds_read_u16 v24, v10 offset:25872
	s_waitcnt lgkmcnt(1)
	v_lshlrev_b32_e32 v26, 16, v0
	v_mul_f32_e32 v0, v25, v26
	s_waitcnt lgkmcnt(0)
	v_lshlrev_b32_e32 v27, 16, v24
	v_cvt_pk_bf16_f32 v0, v0, s0
	ds_write_b16 v10, v0 offset:60416
	v_mul_f32_e32 v0, v28, v27
	v_cvt_pk_bf16_f32 v0, v0, s0
	v_pk_mul_f32 v[24:25], v[2:3], v[26:27]
	ds_write_b16 v10, v0 offset:60688
	v_add_f32_e32 v0, v37, v1
	ds_read_u16 v2, v10 offset:8736
	v_mul_f32_e32 v3, 0x3fb8aa3b, v0
	v_exp_f32_e32 v3, v3
	s_waitcnt lgkmcnt(0)
	v_lshlrev_b32_e32 v2, 16, v2
	v_mul_f32_e32 v2, v3, v2
	v_cvt_pk_bf16_f32 v2, v2, s0
	ds_write_b16 v10, v2 offset:43552
	v_mul_f32_e32 v2, 0xbfb8aa3b, v0
	v_sub_f32_e32 v0, v22, v0
	v_mul_f32_e32 v0, 0x3fb8aa3b, v0
	v_exp_f32_e32 v26, v2
	v_exp_f32_e32 v2, v0
	v_add_f32_e32 v0, v38, v1
	ds_read_u16 v3, v10 offset:9008
	v_mul_f32_e32 v27, 0x3fb8aa3b, v0
	v_exp_f32_e32 v27, v27
	s_waitcnt lgkmcnt(0)
	v_lshlrev_b32_e32 v3, 16, v3
	v_mul_f32_e32 v3, v27, v3
	ds_read_u16 v27, v10 offset:26144
	ds_read_u16 v28, v10 offset:26416
	v_cvt_pk_bf16_f32 v3, v3, s0
	ds_write_b16 v10, v3 offset:43824
	v_mul_f32_e32 v3, 0xbfb8aa3b, v0
	v_exp_f32_e32 v30, v3
	v_sub_f32_e32 v0, v22, v0
	v_mul_f32_e32 v0, 0x3fb8aa3b, v0
	s_waitcnt lgkmcnt(1)
	v_lshlrev_b32_e32 v29, 16, v28
	v_lshlrev_b32_e32 v28, 16, v27
	v_exp_f32_e32 v3, v0
	v_mul_f32_e32 v0, v26, v28
	v_cvt_pk_bf16_f32 v0, v0, s0
	ds_write_b16 v10, v0 offset:60960
	v_mul_f32_e32 v0, v30, v29
	v_cvt_pk_bf16_f32 v0, v0, s0
	v_pk_mul_f32 v[26:27], v[2:3], v[28:29]
	ds_write_b16 v10, v0 offset:61232
	v_add_f32_e32 v0, v39, v1
	ds_read_u16 v2, v10 offset:9280
	v_mul_f32_e32 v3, 0x3fb8aa3b, v0
	v_exp_f32_e32 v3, v3
	s_waitcnt lgkmcnt(0)
	v_lshlrev_b32_e32 v2, 16, v2
	v_mul_f32_e32 v2, v3, v2
	v_cvt_pk_bf16_f32 v2, v2, s0
	ds_write_b16 v10, v2 offset:44096
	v_mul_f32_e32 v2, 0xbfb8aa3b, v0
	v_sub_f32_e32 v0, v22, v0
	v_mul_f32_e32 v0, 0x3fb8aa3b, v0
	v_exp_f32_e32 v28, v2
	v_exp_f32_e32 v2, v0
	v_add_f32_e32 v0, v41, v1
	ds_read_u16 v3, v10 offset:9552
	v_mul_f32_e32 v29, 0x3fb8aa3b, v0
	v_exp_f32_e32 v29, v29
	s_waitcnt lgkmcnt(0)
	v_lshlrev_b32_e32 v3, 16, v3
	v_mul_f32_e32 v3, v29, v3
	v_cvt_pk_bf16_f32 v3, v3, s0
	ds_write_b16 v10, v3 offset:44368
	v_mul_f32_e32 v3, 0xbfb8aa3b, v0
	v_sub_f32_e32 v0, v22, v0
	v_mul_f32_e32 v0, 0x3fb8aa3b, v0
	v_exp_f32_e32 v32, v3
	v_exp_f32_e32 v3, v0
	ds_read_u16 v0, v10 offset:26688
	ds_read_u16 v29, v10 offset:26960
	s_waitcnt lgkmcnt(1)
	v_lshlrev_b32_e32 v30, 16, v0
	v_mul_f32_e32 v0, v28, v30
	s_waitcnt lgkmcnt(0)
	v_lshlrev_b32_e32 v31, 16, v29
	v_cvt_pk_bf16_f32 v0, v0, s0
	ds_write_b16 v10, v0 offset:61504
	v_mul_f32_e32 v0, v32, v31
	v_cvt_pk_bf16_f32 v0, v0, s0
	v_pk_mul_f32 v[28:29], v[2:3], v[30:31]
	ds_write_b16 v10, v0 offset:61776
	v_add_f32_e32 v0, v49, v1
	ds_read_u16 v2, v10 offset:9824
	v_mul_f32_e32 v3, 0x3fb8aa3b, v0
	v_exp_f32_e32 v3, v3
	s_waitcnt lgkmcnt(0)
	v_lshlrev_b32_e32 v2, 16, v2
	v_mul_f32_e32 v2, v3, v2
	v_cvt_pk_bf16_f32 v2, v2, s0
	ds_write_b16 v10, v2 offset:44640
	v_mul_f32_e32 v2, 0xbfb8aa3b, v0
	v_sub_f32_e32 v0, v22, v0
	v_mul_f32_e32 v0, 0x3fb8aa3b, v0
	v_exp_f32_e32 v30, v2
	v_exp_f32_e32 v2, v0
	v_add_f32_e32 v0, v51, v1
	ds_read_u16 v3, v10 offset:10096
	v_mul_f32_e32 v31, 0x3fb8aa3b, v0
	v_exp_f32_e32 v31, v31
	s_waitcnt lgkmcnt(0)
	v_lshlrev_b32_e32 v3, 16, v3
	v_mul_f32_e32 v3, v31, v3
	v_cvt_pk_bf16_f32 v3, v3, s0
	ds_write_b16 v10, v3 offset:44912
	v_mul_f32_e32 v3, 0xbfb8aa3b, v0
	v_sub_f32_e32 v0, v22, v0
	v_mul_f32_e32 v0, 0x3fb8aa3b, v0
	v_exp_f32_e32 v34, v3
	v_exp_f32_e32 v3, v0
	ds_read_u16 v0, v10 offset:27232
	ds_read_u16 v31, v10 offset:27504
	s_waitcnt lgkmcnt(1)
	v_lshlrev_b32_e32 v32, 16, v0
	v_mul_f32_e32 v0, v30, v32
	s_waitcnt lgkmcnt(0)
	v_lshlrev_b32_e32 v33, 16, v31
	v_cvt_pk_bf16_f32 v0, v0, s0
	ds_write_b16 v10, v0 offset:62048
	v_mul_f32_e32 v0, v34, v33
	v_cvt_pk_bf16_f32 v0, v0, s0
	v_pk_mul_f32 v[30:31], v[2:3], v[32:33]
	ds_write_b16 v10, v0 offset:62320
	v_add_f32_e32 v0, v40, v1
	ds_read_u16 v2, v10 offset:10368
	v_mul_f32_e32 v3, 0x3fb8aa3b, v0
	v_exp_f32_e32 v3, v3
	s_waitcnt lgkmcnt(0)
	v_lshlrev_b32_e32 v2, 16, v2
	v_mul_f32_e32 v2, v3, v2
	v_cvt_pk_bf16_f32 v2, v2, s0
	ds_write_b16 v10, v2 offset:45184
	v_mul_f32_e32 v2, 0xbfb8aa3b, v0
	v_sub_f32_e32 v0, v22, v0
	v_mul_f32_e32 v0, 0x3fb8aa3b, v0
	v_exp_f32_e32 v32, v2
	v_exp_f32_e32 v2, v0
	v_add_f32_e32 v0, v50, v1
	ds_read_u16 v3, v10 offset:10640
	v_mul_f32_e32 v33, 0x3fb8aa3b, v0
	v_exp_f32_e32 v33, v33
	s_waitcnt lgkmcnt(0)
	v_lshlrev_b32_e32 v3, 16, v3
	v_mul_f32_e32 v3, v33, v3
	v_cvt_pk_bf16_f32 v3, v3, s0
	ds_write_b16 v10, v3 offset:45456
	v_mul_f32_e32 v3, 0xbfb8aa3b, v0
	v_sub_f32_e32 v0, v22, v0
	v_mul_f32_e32 v0, 0x3fb8aa3b, v0
	v_exp_f32_e32 v36, v3
	v_exp_f32_e32 v3, v0
	ds_read_u16 v0, v10 offset:27776
	ds_read_u16 v33, v10 offset:28048
	s_waitcnt lgkmcnt(1)
	v_lshlrev_b32_e32 v34, 16, v0
	v_mul_f32_e32 v0, v32, v34
	s_waitcnt lgkmcnt(0)
	v_lshlrev_b32_e32 v35, 16, v33
	v_cvt_pk_bf16_f32 v0, v0, s0
	ds_write_b16 v10, v0 offset:62592
	v_mul_f32_e32 v0, v36, v35
	v_cvt_pk_bf16_f32 v0, v0, s0
	v_pk_mul_f32 v[32:33], v[2:3], v[34:35]
	ds_write_b16 v10, v0 offset:62864
	v_add_f32_e32 v0, v52, v1
	ds_read_u16 v2, v10 offset:10912
	v_mul_f32_e32 v3, 0x3fb8aa3b, v0
	v_exp_f32_e32 v3, v3
	s_waitcnt lgkmcnt(0)
	v_lshlrev_b32_e32 v2, 16, v2
	v_mul_f32_e32 v2, v3, v2
	v_cvt_pk_bf16_f32 v2, v2, s0
	ds_write_b16 v10, v2 offset:45728
	v_mul_f32_e32 v2, 0xbfb8aa3b, v0
	v_sub_f32_e32 v0, v22, v0
	v_mul_f32_e32 v0, 0x3fb8aa3b, v0
	v_exp_f32_e32 v34, v2
	v_exp_f32_e32 v2, v0
	v_add_f32_e32 v0, v53, v1
	ds_read_u16 v3, v10 offset:11184
	v_mul_f32_e32 v35, 0x3fb8aa3b, v0
	v_exp_f32_e32 v35, v35
	s_waitcnt lgkmcnt(0)
	v_lshlrev_b32_e32 v3, 16, v3
	v_mul_f32_e32 v3, v35, v3
	v_cvt_pk_bf16_f32 v3, v3, s0
	ds_write_b16 v10, v3 offset:46000
	v_mul_f32_e32 v3, 0xbfb8aa3b, v0
	v_sub_f32_e32 v0, v22, v0
	v_mul_f32_e32 v0, 0x3fb8aa3b, v0
	v_exp_f32_e32 v38, v3
	v_exp_f32_e32 v3, v0
	ds_read_u16 v0, v10 offset:28320
	ds_read_u16 v35, v10 offset:28592
	ds_read_u16 v39, v10 offset:29136
	s_waitcnt lgkmcnt(2)
	v_lshlrev_b32_e32 v36, 16, v0
	v_mul_f32_e32 v0, v34, v36
	s_waitcnt lgkmcnt(1)
	v_lshlrev_b32_e32 v37, 16, v35
	v_cvt_pk_bf16_f32 v0, v0, s0
	ds_write_b16 v10, v0 offset:63136
	v_mul_f32_e32 v0, v38, v37
	v_cvt_pk_bf16_f32 v0, v0, s0
	v_pk_mul_f32 v[34:35], v[2:3], v[36:37]
	ds_write_b16 v10, v0 offset:63408
	v_add_f32_e32 v0, v54, v1
	ds_read_u16 v2, v10 offset:11456
	ds_read_u16 v36, v10 offset:28864
	v_mul_f32_e32 v3, 0x3fb8aa3b, v0
	v_exp_f32_e32 v3, v3
	s_waitcnt lgkmcnt(4)
	v_lshlrev_b32_e32 v39, 16, v39
	s_waitcnt lgkmcnt(1)
	v_lshlrev_b32_e32 v2, 16, v2
	v_mul_f32_e32 v2, v3, v2
	v_cvt_pk_bf16_f32 v2, v2, s0
	ds_write_b16 v10, v2 offset:46272
	v_mul_f32_e32 v2, 0xbfb8aa3b, v0
	v_sub_f32_e32 v0, v22, v0
	v_mul_f32_e32 v0, 0x3fb8aa3b, v0
	v_exp_f32_e32 v37, v2
	v_exp_f32_e32 v2, v0
	v_add_f32_e32 v0, v55, v1
	ds_read_u16 v3, v10 offset:11728
	v_mul_f32_e32 v38, 0x3fb8aa3b, v0
	v_exp_f32_e32 v38, v38
	s_waitcnt lgkmcnt(0)
	v_lshlrev_b32_e32 v3, 16, v3
	v_mul_f32_e32 v3, v38, v3
	v_cvt_pk_bf16_f32 v3, v3, s0
	ds_write_b16 v10, v3 offset:46544
	v_mul_f32_e32 v3, 0xbfb8aa3b, v0
	v_exp_f32_e32 v40, v3
	v_sub_f32_e32 v0, v22, v0
	v_mul_f32_e32 v0, 0x3fb8aa3b, v0
	v_lshlrev_b32_e32 v38, 16, v36
	v_exp_f32_e32 v3, v0
	v_mul_f32_e32 v0, v37, v38
	v_cvt_pk_bf16_f32 v0, v0, s0
	ds_write_b16 v10, v0 offset:63680
	v_mul_f32_e32 v0, v40, v39
	v_cvt_pk_bf16_f32 v0, v0, s0
	ds_write_b16 v10, v0 offset:63952
	v_add_f32_e32 v0, v56, v1
	ds_read_u16 v1, v10 offset:12000
	v_pk_mul_f32 v[36:37], v[2:3], v[38:39]
	v_mul_f32_e32 v2, 0x3fb8aa3b, v0
	v_exp_f32_e32 v2, v2
	v_mul_f32_e32 v3, 0x3fb8aa3b, v23
	s_waitcnt lgkmcnt(0)
	v_lshlrev_b32_e32 v1, 16, v1
	v_exp_f32_e32 v3, v3
	v_mul_f32_e32 v1, v2, v1
	v_cvt_pk_bf16_f32 v1, v1, s0
	ds_write_b16 v10, v1 offset:46816
	v_mul_f32_e32 v1, 0xbfb8aa3b, v0
	ds_read_u16 v2, v10 offset:29408
	v_exp_f32_e32 v38, v1
	ds_read_u16 v1, v10 offset:12272
	v_sub_f32_e32 v0, v22, v0
	v_mul_f32_e32 v0, 0x3fb8aa3b, v0
	v_exp_f32_e32 v0, v0
	s_waitcnt lgkmcnt(1)
	v_lshlrev_b32_e32 v2, 16, v2
	s_waitcnt lgkmcnt(0)
	v_lshlrev_b32_e32 v1, 16, v1
	v_mul_f32_e32 v1, v3, v1
	v_cvt_pk_bf16_f32 v1, v1, s0
	ds_read_u16 v3, v10 offset:29680
	ds_write_b16 v10, v1 offset:47088
	v_mul_f32_e32 v1, 0xbfb8aa3b, v23
	v_exp_f32_e32 v39, v1
	v_sub_f32_e32 v1, v22, v23
	v_mul_f32_e32 v1, 0x3fb8aa3b, v1
	v_exp_f32_e32 v1, v1
	v_mul_f32_e32 v23, v38, v2
	s_waitcnt lgkmcnt(1)
	v_lshlrev_b32_e32 v3, 16, v3
	v_cvt_pk_bf16_f32 v23, v23, s0
	ds_write_b16 v10, v23 offset:64224
	v_mul_f32_e32 v23, v39, v3
	v_cvt_pk_bf16_f32 v23, v23, s0
	v_pk_mul_f32 v[38:39], v[0:1], v[2:3]
	ds_write_b16 v10, v23 offset:64496
	s_cbranch_scc0 .LBB0_333
	v_pk_mov_b32 v[0:1], v[38:39], v[38:39] op_sel:[1,0]
	v_pk_mov_b32 v[2:3], v[28:29], v[28:29] op_sel:[1,0]
	v_cvt_pk_bf16_f32 v50, v0, v1
	v_pk_mov_b32 v[0:1], v[36:37], v[36:37] op_sel:[1,0]
	v_pk_mov_b32 v[40:41], v[24:25], v[24:25] op_sel:[1,0]
	v_cvt_pk_bf16_f32 v51, v0, v1
	v_pk_mov_b32 v[0:1], v[34:35], v[34:35] op_sel:[1,0]
	s_mov_b64 s[12:13], 0
	v_cvt_pk_bf16_f32 v52, v0, v1
	v_pk_mov_b32 v[0:1], v[32:33], v[32:33] op_sel:[1,0]
	s_nop 0
	v_cvt_pk_bf16_f32 v53, v0, v1
	v_pk_mov_b32 v[0:1], v[30:31], v[30:31] op_sel:[1,0]
	s_nop 0
	v_cvt_pk_bf16_f32 v0, v0, v1
	v_cvt_pk_bf16_f32 v1, v2, v3
	v_pk_mov_b32 v[2:3], v[26:27], v[26:27] op_sel:[1,0]
	s_nop 0
	v_cvt_pk_bf16_f32 v2, v2, v3
	v_cvt_pk_bf16_f32 v3, v40, v41
	v_lshl_add_u64 v[40:41], v[14:15], 0, s[26:27]
	global_store_dwordx4 v[40:41], v[50:53], off
